# P0 adaLN: silu(c) fill loop 8 elements per pass with batched loads; accumulate loop weight loads flat->global (on v64)
# speedup vs baseline: 1.0178x; 1.0031x over previous
; #define LAS __attribute__((address_space(3)))
; __device__ __forceinline__ float siluf_(float x) { return x * sigmoidf_(x); }
; __device__ __forceinline__ int lane_id_() { int l; asm volatile("v_mbcnt_lo_u32_b32 %0, -1, 0\n\tv_mbcnt_hi_u32_b32 %0, -1, %0" : "=v"(l)); return l; }
; #define F_c INF(1)
; __device__ __forceinline__ void p0_prologue(const Ctx& F) {
;     ...
;         LAS float* cs = (LAS float*)F.lds;
;         for (int e = (F.wid * 64 + lane_id_()); e < 32768; e += NTHREADS) { const int k = e >> 5, b = e & 31; cs[e] = siluf_(F_c[b * 1024 + k]); }
;         __syncthreads();
.LBB0_10:
	v_ashrrev_i32_e32 v6, 5, v2
	v_and_b32_e32 v7, 0x7c00, v5
	v_add_u32_e32 v6, v7, v6
	v_ashrrev_i32_e32 v7, 31, v6
	s_waitcnt lgkmcnt(0)
	v_lshl_add_u64 v[6:7], v[6:7], 2, s[14:15]
	global_load_dword v100, v[6:7], off
	global_load_dword v101, v[6:7], off offset:64
	global_load_dword v102, v[6:7], off offset:128
	global_load_dword v103, v[6:7], off offset:192
	global_load_dword v104, v[6:7], off offset:256
	global_load_dword v105, v[6:7], off offset:320
	global_load_dword v106, v[6:7], off offset:384
	global_load_dword v107, v[6:7], off offset:448
	v_cmp_lt_i32_e32 vcc, 0x6fff, v2
	v_add_u32_e32 v2, 0x1000, v2
	v_add_u32_e32 v5, 0x400000, v5
	s_or_b64 s[16:17], vcc, s[16:17]
	s_waitcnt vmcnt(7)
	v_mul_f32_e32 v108, 0xbfb8aa3b, v100
	v_exp_f32_e32 v108, v108
	s_nop 0
	v_add_f32_e32 v108, 1.0, v108
	v_rcp_f32_e32 v108, v108
	s_nop 0
	v_mul_f32_e32 v108, v100, v108
	ds_write_b32 v4, v108
	s_waitcnt vmcnt(6)
	v_mul_f32_e32 v108, 0xbfb8aa3b, v101
	v_exp_f32_e32 v108, v108
	s_nop 0
	v_add_f32_e32 v108, 1.0, v108
	v_rcp_f32_e32 v108, v108
	s_nop 0
	v_mul_f32_e32 v108, v101, v108
	ds_write_b32 v4, v108 offset:2048
	s_waitcnt vmcnt(5)
	v_mul_f32_e32 v108, 0xbfb8aa3b, v102
	v_exp_f32_e32 v108, v108
	s_nop 0
	v_add_f32_e32 v108, 1.0, v108
	v_rcp_f32_e32 v108, v108
	s_nop 0
	v_mul_f32_e32 v108, v102, v108
	ds_write_b32 v4, v108 offset:4096
	s_waitcnt vmcnt(4)
	v_mul_f32_e32 v108, 0xbfb8aa3b, v103
	v_exp_f32_e32 v108, v108
	s_nop 0
	v_add_f32_e32 v108, 1.0, v108
	v_rcp_f32_e32 v108, v108
	s_nop 0
	v_mul_f32_e32 v108, v103, v108
	ds_write_b32 v4, v108 offset:6144
	s_waitcnt vmcnt(3)
	v_mul_f32_e32 v108, 0xbfb8aa3b, v104
	v_exp_f32_e32 v108, v108
	s_nop 0
	v_add_f32_e32 v108, 1.0, v108
	v_rcp_f32_e32 v108, v108
	s_nop 0
	v_mul_f32_e32 v108, v104, v108
	ds_write_b32 v4, v108 offset:8192
	s_waitcnt vmcnt(2)
	v_mul_f32_e32 v108, 0xbfb8aa3b, v105
	v_exp_f32_e32 v108, v108
	s_nop 0
	v_add_f32_e32 v108, 1.0, v108
	v_rcp_f32_e32 v108, v108
	s_nop 0
	v_mul_f32_e32 v108, v105, v108
	ds_write_b32 v4, v108 offset:10240
	s_waitcnt vmcnt(1)
	v_mul_f32_e32 v108, 0xbfb8aa3b, v106
	v_exp_f32_e32 v108, v108
	s_nop 0
	v_add_f32_e32 v108, 1.0, v108
	v_rcp_f32_e32 v108, v108
	s_nop 0
	v_mul_f32_e32 v108, v106, v108
	ds_write_b32 v4, v108 offset:12288
	s_waitcnt vmcnt(0)
	v_mul_f32_e32 v108, 0xbfb8aa3b, v107
	v_exp_f32_e32 v108, v108
	s_nop 0
	v_add_f32_e32 v108, 1.0, v108
	v_rcp_f32_e32 v108, v108
	s_nop 0
	v_mul_f32_e32 v108, v107, v108
	ds_write_b32 v4, v108 offset:14336
	v_add_u32_e32 v4, 0x4000, v4
	s_andn2_b64 exec, exec, s[16:17]
	s_cbranch_execnz .LBB0_10

; #define LAS __attribute__((address_space(3)))
; __device__ __forceinline__ void p0_prologue(const Ctx& F) {
;     ...
;         for (int k8 = 0; k8 < 128; k8 += 8) {
;             float wv[8];
; #pragma unroll
;             for (int u = 0; u < 8; ++u) wv[u] = wp[(size_t)(k8 + u) * 6144];
; #pragma unroll
;             for (int u = 0; u < 8; ++u) { const float w = wv[u]; const LAS f32x4* cr = (const LAS f32x4*)(cs + (kp * 128 + k8 + u) * 32);
; #pragma unroll
;                 for (int b4 = 0; b4 < 8; ++b4) { const f32x4 cv = cr[b4]; acc[4 * b4] += cv[0] * w; acc[4 * b4 + 1] += cv[1] * w; acc[4 * b4 + 2] += cv[2] * w; acc[4 * b4 + 3] += cv[3] * w; } }
.LBB0_12:
	v_add_co_u32_e32 v6, vcc, s24, v4
	ds_read_b128 v[50:53], v48
	ds_read_b128 v[54:57], v48 offset:16
	v_addc_co_u32_e32 v7, vcc, -1, v5, vcc
	v_add_co_u32_e32 v10, vcc, s25, v4
	s_add_i32 s15, s15, 8
	s_nop 0
	v_addc_co_u32_e32 v11, vcc, -1, v5, vcc
	global_load_dword v40, v[6:7], off
	global_load_dword v41, v[10:11], off
	v_add_co_u32_e32 v62, vcc, s26, v4
	ds_read_b128 v[58:61], v48 offset:32
	s_nop 0
	v_addc_co_u32_e32 v63, vcc, -1, v5, vcc
	v_add_co_u32_e32 v64, vcc, s27, v4
	s_cmpk_gt_u32 s15, 0x77
	s_nop 0
	v_addc_co_u32_e32 v65, vcc, -1, v5, vcc
	v_add_co_u32_e32 v66, vcc, s28, v4
	s_waitcnt vmcnt(0) lgkmcnt(0)
	v_pk_fma_f32 v[42:43], v[40:41], v[50:51], v[42:43] op_sel_hi:[0,1,1]
	v_addc_co_u32_e32 v67, vcc, -1, v5, vcc
	v_add_co_u32_e32 v68, vcc, s29, v4
	v_pk_fma_f32 v[44:45], v[40:41], v[52:53], v[44:45] op_sel_hi:[0,1,1]
	s_nop 0
	v_addc_co_u32_e32 v69, vcc, -1, v5, vcc
	v_add_co_u32_e32 v70, vcc, s30, v4
	v_pk_fma_f32 v[54:55], v[40:41], v[54:55], v[32:33] op_sel_hi:[0,1,1]
	s_nop 0
	v_addc_co_u32_e32 v71, vcc, -1, v5, vcc
	global_load_dword v22, v[62:63], off
	global_load_dword v23, v[64:65], off
	global_load_dword v10, v[66:67], off
	global_load_dword v11, v[68:69], off
	global_load_dword v6, v[70:71], off
	global_load_dword v2, v[4:5], off
	ds_read_b128 v[50:53], v48 offset:48
	v_pk_fma_f32 v[56:57], v[40:41], v[56:57], v[34:35] op_sel_hi:[0,1,1]
	ds_read_b128 v[32:35], v48 offset:64
	v_pk_fma_f32 v[58:59], v[40:41], v[58:59], v[24:25] op_sel_hi:[0,1,1]
	v_pk_fma_f32 v[60:61], v[40:41], v[60:61], v[26:27] op_sel_hi:[0,1,1]
	ds_read_b128 v[24:27], v48 offset:80
	s_waitcnt lgkmcnt(0)
	v_pk_fma_f32 v[50:51], v[40:41], v[50:51], v[18:19] op_sel_hi:[0,1,1]
	v_pk_fma_f32 v[52:53], v[40:41], v[52:53], v[20:21] op_sel_hi:[0,1,1]
	ds_read_b128 v[18:21], v48 offset:96
	v_pk_fma_f32 v[62:63], v[40:41], v[32:33], v[12:13] op_sel_hi:[0,1,1]
	v_pk_fma_f32 v[64:65], v[40:41], v[34:35], v[14:15] op_sel_hi:[0,1,1]
	ds_read_b128 v[32:35], v48 offset:112
	ds_read_b128 v[12:15], v48 offset:128
	s_waitcnt lgkmcnt(0)
	v_pk_fma_f32 v[28:29], v[40:41], v[18:19], v[28:29] op_sel_hi:[0,1,1]
	v_pk_fma_f32 v[30:31], v[40:41], v[20:21], v[30:31] op_sel_hi:[0,1,1]
	ds_read_b128 v[18:21], v48 offset:144
	v_mov_b32_e32 v66, v41
	v_pk_fma_f32 v[42:43], v[66:67], v[12:13], v[42:43] op_sel_hi:[0,1,1]
	v_pk_fma_f32 v[44:45], v[66:67], v[14:15], v[44:45] op_sel_hi:[0,1,1]
	ds_read_b128 v[12:15], v48 offset:160
	s_waitcnt lgkmcnt(0)
	v_pk_fma_f32 v[54:55], v[66:67], v[18:19], v[54:55] op_sel_hi:[0,1,1]
	v_pk_fma_f32 v[56:57], v[66:67], v[20:21], v[56:57] op_sel_hi:[0,1,1]
	ds_read_b128 v[18:21], v48 offset:176
	v_pk_fma_f32 v[36:37], v[40:41], v[24:25], v[36:37] op_sel_hi:[0,1,1]
	v_pk_fma_f32 v[38:39], v[40:41], v[26:27], v[38:39] op_sel_hi:[0,1,1]
	v_pk_fma_f32 v[58:59], v[66:67], v[12:13], v[58:59] op_sel_hi:[0,1,1]
	v_pk_fma_f32 v[60:61], v[66:67], v[14:15], v[60:61] op_sel_hi:[0,1,1]
	ds_read_b128 v[12:15], v48 offset:192
	s_waitcnt lgkmcnt(0)
	v_pk_fma_f32 v[50:51], v[66:67], v[18:19], v[50:51] op_sel_hi:[0,1,1]
	v_pk_fma_f32 v[52:53], v[66:67], v[20:21], v[52:53] op_sel_hi:[0,1,1]
	ds_read_b128 v[18:21], v48 offset:208
	ds_read_b128 v[24:27], v48 offset:240
	v_pk_fma_f32 v[62:63], v[66:67], v[12:13], v[62:63] op_sel_hi:[0,1,1]
	v_pk_fma_f32 v[64:65], v[66:67], v[14:15], v[64:65] op_sel_hi:[0,1,1]
	v_pk_fma_f32 v[32:33], v[40:41], v[32:33], v[16:17] op_sel_hi:[0,1,1]
	v_mul_f32_e32 v14, v40, v34
	s_waitcnt lgkmcnt(0)
	v_mul_f32_e32 v12, v41, v26
	v_mov_b32_e32 v26, v35
	v_pk_fma_f32 v[34:35], v[66:67], v[18:19], v[36:37] op_sel_hi:[0,1,1]
	ds_read_b128 v[16:19], v48 offset:224
	v_pk_mul_f32 v[36:37], v[40:41], v[26:27]
	v_pk_fma_f32 v[32:33], v[66:67], v[24:25], v[32:33] op_sel_hi:[0,1,1]
	ds_read_b128 v[24:27], v48 offset:272
	v_pk_fma_f32 v[20:21], v[66:67], v[20:21], v[38:39] op_sel_hi:[0,1,1]
	s_waitcnt lgkmcnt(0)
	v_pk_fma_f32 v[28:29], v[66:67], v[16:17], v[28:29] op_sel_hi:[0,1,1]
	v_pk_fma_f32 v[30:31], v[66:67], v[18:19], v[30:31] op_sel_hi:[0,1,1]
	ds_read_b128 v[16:19], v48 offset:256
	v_mov_b32_e32 v15, v36
	v_mov_b32_e32 v13, v37
	v_pk_add_f32 v[8:9], v[8:9], v[14:15]
	v_lshl_add_u64 v[4:5], v[4:5], 0, s[8:9]
	v_pk_add_f32 v[12:13], v[8:9], v[12:13]
	s_waitcnt vmcnt(0) lgkmcnt(0)
	v_pk_fma_f32 v[38:39], v[22:23], v[16:17], v[42:43] op_sel_hi:[0,1,1]
	v_pk_fma_f32 v[40:41], v[22:23], v[18:19], v[44:45] op_sel_hi:[0,1,1]
	ds_read_b128 v[16:19], v48 offset:288
	v_pk_fma_f32 v[42:43], v[22:23], v[24:25], v[54:55] op_sel_hi:[0,1,1]
	v_pk_fma_f32 v[44:45], v[22:23], v[26:27], v[56:57] op_sel_hi:[0,1,1]
	ds_read_b128 v[24:27], v48 offset:304
	v_mov_b32_e32 v66, v23
	s_waitcnt lgkmcnt(1)
	v_pk_fma_f32 v[54:55], v[22:23], v[16:17], v[58:59] op_sel_hi:[0,1,1]
	v_pk_fma_f32 v[56:57], v[22:23], v[18:19], v[60:61] op_sel_hi:[0,1,1]
	ds_read_b128 v[16:19], v48 offset:320
	s_waitcnt lgkmcnt(1)
	v_pk_fma_f32 v[50:51], v[22:23], v[24:25], v[50:51] op_sel_hi:[0,1,1]
	v_pk_fma_f32 v[52:53], v[22:23], v[26:27], v[52:53] op_sel_hi:[0,1,1]
	ds_read_b128 v[24:27], v48 offset:336
	s_waitcnt lgkmcnt(1)
	v_pk_fma_f32 v[58:59], v[22:23], v[16:17], v[62:63] op_sel_hi:[0,1,1]
	v_pk_fma_f32 v[60:61], v[22:23], v[18:19], v[64:65] op_sel_hi:[0,1,1]
	ds_read_b128 v[16:19], v48 offset:352
	s_waitcnt lgkmcnt(1)
	v_pk_fma_f32 v[34:35], v[22:23], v[24:25], v[34:35] op_sel_hi:[0,1,1]
	v_pk_fma_f32 v[20:21], v[22:23], v[26:27], v[20:21] op_sel_hi:[0,1,1]
	ds_read_b128 v[24:27], v48 offset:368
	s_waitcnt lgkmcnt(1)
	v_pk_fma_f32 v[62:63], v[22:23], v[16:17], v[28:29] op_sel_hi:[0,1,1]
	v_pk_fma_f32 v[64:65], v[22:23], v[18:19], v[30:31] op_sel_hi:[0,1,1]
	ds_read_b128 v[16:19], v48 offset:384
	ds_read_b128 v[28:31], v48 offset:400
	s_waitcnt lgkmcnt(1)
; #define LAS __attribute__((address_space(3)))
; __device__ __forceinline__ void p0_prologue(const Ctx& F) {
;     ...
; #pragma unroll
;             for (int u = 0; u < 8; ++u) { const float w = wv[u]; const LAS f32x4* cr = (const LAS f32x4*)(cs + (kp * 128 + k8 + u) * 32);
; #pragma unroll
;                 for (int b4 = 0; b4 < 8; ++b4) { const f32x4 cv = cr[b4]; acc[4 * b4] += cv[0] * w; acc[4 * b4 + 1] += cv[1] * w; acc[4 * b4 + 2] += cv[2] * w; acc[4 * b4 + 3] += cv[3] * w; } }
	v_pk_fma_f32 v[38:39], v[66:67], v[16:17], v[38:39] op_sel_hi:[0,1,1]
	v_pk_fma_f32 v[40:41], v[66:67], v[18:19], v[40:41] op_sel_hi:[0,1,1]
	s_waitcnt lgkmcnt(0)
	v_pk_fma_f32 v[42:43], v[66:67], v[28:29], v[42:43] op_sel_hi:[0,1,1]
	v_pk_fma_f32 v[44:45], v[66:67], v[30:31], v[44:45] op_sel_hi:[0,1,1]
	ds_read_b128 v[16:19], v48 offset:416
	ds_read_b128 v[28:31], v48 offset:432
	s_waitcnt lgkmcnt(1)
	v_pk_fma_f32 v[54:55], v[66:67], v[16:17], v[54:55] op_sel_hi:[0,1,1]
	v_pk_fma_f32 v[56:57], v[66:67], v[18:19], v[56:57] op_sel_hi:[0,1,1]
	s_waitcnt lgkmcnt(0)
	v_pk_fma_f32 v[50:51], v[66:67], v[28:29], v[50:51] op_sel_hi:[0,1,1]
	v_pk_fma_f32 v[52:53], v[66:67], v[30:31], v[52:53] op_sel_hi:[0,1,1]
	ds_read_b128 v[16:19], v48 offset:448
	ds_read_b128 v[28:31], v48 offset:464
	s_waitcnt lgkmcnt(1)
	v_pk_fma_f32 v[58:59], v[66:67], v[16:17], v[58:59] op_sel_hi:[0,1,1]
	v_pk_fma_f32 v[60:61], v[66:67], v[18:19], v[60:61] op_sel_hi:[0,1,1]
	s_waitcnt lgkmcnt(0)
	v_pk_fma_f32 v[34:35], v[66:67], v[28:29], v[34:35] op_sel_hi:[0,1,1]
	v_pk_fma_f32 v[68:69], v[66:67], v[30:31], v[20:21] op_sel_hi:[0,1,1]
	ds_read_b128 v[16:19], v48 offset:480
	ds_read_b128 v[28:31], v48 offset:496
	s_waitcnt lgkmcnt(1)
	v_pk_fma_f32 v[62:63], v[66:67], v[16:17], v[62:63] op_sel_hi:[0,1,1]
	s_waitcnt lgkmcnt(0)
	v_mul_f32_e32 v70, v23, v30
	v_mov_b32_e32 v30, v27
	v_pk_fma_f32 v[16:17], v[22:23], v[24:25], v[32:33] op_sel_hi:[0,1,1]
	v_pk_fma_f32 v[64:65], v[66:67], v[18:19], v[64:65] op_sel_hi:[0,1,1]
	v_mul_f32_e32 v32, v22, v26
	v_pk_mul_f32 v[72:73], v[22:23], v[30:31]
	v_pk_fma_f32 v[66:67], v[66:67], v[28:29], v[16:17] op_sel_hi:[0,1,1]
	ds_read_b128 v[16:19], v48 offset:512
	ds_read_b128 v[20:23], v48 offset:528
	v_mov_b32_e32 v33, v72
	v_mov_b32_e32 v71, v73
	v_pk_add_f32 v[12:13], v[12:13], v[32:33]
	s_waitcnt lgkmcnt(1)
	v_pk_fma_f32 v[28:29], v[10:11], v[16:17], v[38:39] op_sel_hi:[0,1,1]
	v_pk_fma_f32 v[30:31], v[10:11], v[18:19], v[40:41] op_sel_hi:[0,1,1]
	s_waitcnt lgkmcnt(0)
	v_pk_fma_f32 v[38:39], v[10:11], v[20:21], v[42:43] op_sel_hi:[0,1,1]
	v_pk_fma_f32 v[40:41], v[10:11], v[22:23], v[44:45] op_sel_hi:[0,1,1]
	ds_read_b128 v[16:19], v48 offset:544
	ds_read_b128 v[20:23], v48 offset:560
	v_pk_add_f32 v[70:71], v[12:13], v[70:71]
	s_waitcnt lgkmcnt(1)
	v_pk_fma_f32 v[42:43], v[10:11], v[16:17], v[54:55] op_sel_hi:[0,1,1]
	v_pk_fma_f32 v[44:45], v[10:11], v[18:19], v[56:57] op_sel_hi:[0,1,1]
	s_waitcnt lgkmcnt(0)
	v_pk_fma_f32 v[50:51], v[10:11], v[20:21], v[50:51] op_sel_hi:[0,1,1]
	v_pk_fma_f32 v[52:53], v[10:11], v[22:23], v[52:53] op_sel_hi:[0,1,1]
	ds_read_b128 v[16:19], v48 offset:576
	ds_read_b128 v[20:23], v48 offset:592
	s_waitcnt lgkmcnt(1)
	v_pk_fma_f32 v[54:55], v[10:11], v[16:17], v[58:59] op_sel_hi:[0,1,1]
	v_pk_fma_f32 v[56:57], v[10:11], v[18:19], v[60:61] op_sel_hi:[0,1,1]
	ds_read_b128 v[16:19], v48 offset:608
	ds_read_b128 v[24:27], v48 offset:624
	s_waitcnt lgkmcnt(2)
	v_pk_fma_f32 v[34:35], v[10:11], v[20:21], v[34:35] op_sel_hi:[0,1,1]
	v_pk_fma_f32 v[58:59], v[10:11], v[22:23], v[68:69] op_sel_hi:[0,1,1]
	s_waitcnt lgkmcnt(1)
	v_pk_fma_f32 v[60:61], v[10:11], v[16:17], v[62:63] op_sel_hi:[0,1,1]
	v_pk_fma_f32 v[62:63], v[10:11], v[18:19], v[64:65] op_sel_hi:[0,1,1]
	ds_read_b128 v[16:19], v48 offset:640
	ds_read_b128 v[20:23], v48 offset:656
	v_mov_b32_e32 v64, v11
	s_waitcnt lgkmcnt(1)
	v_pk_fma_f32 v[68:69], v[64:65], v[16:17], v[28:29] op_sel_hi:[0,1,1]
	v_pk_fma_f32 v[74:75], v[64:65], v[18:19], v[30:31] op_sel_hi:[0,1,1]
	s_waitcnt lgkmcnt(0)
	v_pk_fma_f32 v[38:39], v[64:65], v[20:21], v[38:39] op_sel_hi:[0,1,1]
	v_pk_fma_f32 v[76:77], v[64:65], v[22:23], v[40:41] op_sel_hi:[0,1,1]
	ds_read_b128 v[16:19], v48 offset:672
	ds_read_b128 v[20:23], v48 offset:688
	v_mul_f32_e32 v40, v10, v26
	s_waitcnt lgkmcnt(1)
	v_pk_fma_f32 v[42:43], v[64:65], v[16:17], v[42:43] op_sel_hi:[0,1,1]
	v_pk_fma_f32 v[44:45], v[64:65], v[18:19], v[44:45] op_sel_hi:[0,1,1]
	s_waitcnt lgkmcnt(0)
	v_pk_fma_f32 v[50:51], v[64:65], v[20:21], v[50:51] op_sel_hi:[0,1,1]
	v_pk_fma_f32 v[52:53], v[64:65], v[22:23], v[52:53] op_sel_hi:[0,1,1]
	ds_read_b128 v[16:19], v48 offset:704
	ds_read_b128 v[20:23], v48 offset:720
	s_waitcnt lgkmcnt(1)
	v_pk_fma_f32 v[54:55], v[64:65], v[16:17], v[54:55] op_sel_hi:[0,1,1]
	v_pk_fma_f32 v[56:57], v[64:65], v[18:19], v[56:57] op_sel_hi:[0,1,1]
	ds_read_b128 v[16:19], v48 offset:736
	ds_read_b128 v[28:31], v48 offset:752
	s_waitcnt lgkmcnt(2)
	v_pk_fma_f32 v[20:21], v[64:65], v[20:21], v[34:35] op_sel_hi:[0,1,1]
	v_pk_fma_f32 v[34:35], v[64:65], v[22:23], v[58:59] op_sel_hi:[0,1,1]
	ds_read_b128 v[12:15], v48 offset:912
	s_waitcnt lgkmcnt(2)
	v_pk_fma_f32 v[58:59], v[64:65], v[16:17], v[60:61] op_sel_hi:[0,1,1]
	v_pk_fma_f32 v[16:17], v[10:11], v[24:25], v[66:67] op_sel_hi:[0,1,1]
	v_pk_fma_f32 v[60:61], v[64:65], v[18:19], v[62:63] op_sel_hi:[0,1,1]
	s_waitcnt lgkmcnt(1)
	v_mul_f32_e32 v22, v11, v30
	v_mov_b32_e32 v30, v27
	v_pk_fma_f32 v[28:29], v[64:65], v[28:29], v[16:17] op_sel_hi:[0,1,1]
	ds_read_b128 v[16:19], v48 offset:768
	ds_read_b128 v[24:27], v48 offset:784
	v_pk_mul_f32 v[10:11], v[10:11], v[30:31]
	s_waitcnt lgkmcnt(1)
	v_pk_fma_f32 v[30:31], v[6:7], v[16:17], v[68:69] op_sel_hi:[0,1,1]
	v_pk_fma_f32 v[36:37], v[6:7], v[18:19], v[74:75] op_sel_hi:[0,1,1]
	ds_read_b128 v[16:19], v48 offset:800
	s_waitcnt lgkmcnt(1)
	v_pk_fma_f32 v[38:39], v[6:7], v[24:25], v[38:39] op_sel_hi:[0,1,1]
	v_pk_fma_f32 v[62:63], v[6:7], v[26:27], v[76:77] op_sel_hi:[0,1,1]
	ds_read_b128 v[24:27], v48 offset:816
	v_mov_b32_e32 v41, v10
	v_mov_b32_e32 v23, v11
	s_waitcnt lgkmcnt(1)
; #define LAS __attribute__((address_space(3)))
; __device__ __forceinline__ void p0_prologue(const Ctx& F) {
;     ...
; #pragma unroll
;             for (int u = 0; u < 8; ++u) { const float w = wv[u]; const LAS f32x4* cr = (const LAS f32x4*)(cs + (kp * 128 + k8 + u) * 32);
; #pragma unroll
;                 for (int b4 = 0; b4 < 8; ++b4) { const f32x4 cv = cr[b4]; acc[4 * b4] += cv[0] * w; acc[4 * b4 + 1] += cv[1] * w; acc[4 * b4 + 2] += cv[2] * w; acc[4 * b4 + 3] += cv[3] * w; } }
;         }
;         __syncthreads();
;         LAS float* red = (LAS float*)F.lds;
; #pragma unroll
;         for (int b = 0; b < 32; ++b) red[(kp * 32 + b) * 64 + n] = acc[b];
;         __syncthreads();
	v_pk_fma_f32 v[64:65], v[6:7], v[16:17], v[42:43] op_sel_hi:[0,1,1]
	v_pk_fma_f32 v[66:67], v[6:7], v[18:19], v[44:45] op_sel_hi:[0,1,1]
	ds_read_b128 v[16:19], v48 offset:832
	s_waitcnt lgkmcnt(1)
	v_pk_fma_f32 v[68:69], v[6:7], v[24:25], v[50:51] op_sel_hi:[0,1,1]
	v_pk_fma_f32 v[72:73], v[6:7], v[26:27], v[52:53] op_sel_hi:[0,1,1]
	ds_read_b128 v[24:27], v48 offset:848
	ds_read_b128 v[8:11], v48 offset:896
	s_waitcnt lgkmcnt(2)
	v_pk_fma_f32 v[54:55], v[6:7], v[16:17], v[54:55] op_sel_hi:[0,1,1]
	v_pk_fma_f32 v[56:57], v[6:7], v[18:19], v[56:57] op_sel_hi:[0,1,1]
	ds_read_b128 v[16:19], v48 offset:864
	s_waitcnt lgkmcnt(2)
	v_pk_fma_f32 v[74:75], v[6:7], v[24:25], v[20:21] op_sel_hi:[0,1,1]
	v_pk_fma_f32 v[76:77], v[6:7], v[26:27], v[34:35] op_sel_hi:[0,1,1]
	ds_read_b128 v[24:27], v48 offset:880
	ds_read_b128 v[50:53], v48 offset:1008
	s_waitcnt lgkmcnt(3)
	v_pk_fma_f32 v[42:43], v[2:3], v[8:9], v[30:31] op_sel_hi:[0,1,1]
	v_pk_fma_f32 v[44:45], v[2:3], v[10:11], v[36:37] op_sel_hi:[0,1,1]
	ds_read_b128 v[8:11], v48 offset:928
	s_waitcnt lgkmcnt(3)
	v_pk_fma_f32 v[16:17], v[6:7], v[16:17], v[58:59] op_sel_hi:[0,1,1]
	v_pk_fma_f32 v[58:59], v[6:7], v[18:19], v[60:61] op_sel_hi:[0,1,1]
	s_waitcnt lgkmcnt(2)
	v_mul_f32_e32 v60, v6, v26
	s_waitcnt lgkmcnt(1)
	v_mul_f32_e32 v78, v2, v52
	v_mov_b32_e32 v52, v27
	v_pk_fma_f32 v[80:81], v[6:7], v[24:25], v[28:29] op_sel_hi:[0,1,1]
	v_pk_fma_f32 v[32:33], v[2:3], v[12:13], v[38:39] op_sel_hi:[0,1,1]
	v_pk_fma_f32 v[34:35], v[2:3], v[14:15], v[62:63] op_sel_hi:[0,1,1]
	ds_read_b128 v[12:15], v48 offset:944
	s_waitcnt lgkmcnt(1)
	v_pk_fma_f32 v[24:25], v[2:3], v[8:9], v[64:65] op_sel_hi:[0,1,1]
	v_pk_fma_f32 v[26:27], v[2:3], v[10:11], v[66:67] op_sel_hi:[0,1,1]
	ds_read_b128 v[8:11], v48 offset:960
	ds_read_b128 v[28:31], v48 offset:976
	s_waitcnt lgkmcnt(2)
	v_pk_fma_f32 v[18:19], v[2:3], v[12:13], v[68:69] op_sel_hi:[0,1,1]
	v_pk_fma_f32 v[20:21], v[2:3], v[14:15], v[72:73] op_sel_hi:[0,1,1]
	v_mov_b32_e32 v7, v2
	s_waitcnt lgkmcnt(1)
	v_pk_fma_f32 v[12:13], v[2:3], v[8:9], v[54:55] op_sel_hi:[0,1,1]
	v_pk_fma_f32 v[14:15], v[2:3], v[10:11], v[56:57] op_sel_hi:[0,1,1]
	ds_read_b128 v[8:11], v48 offset:992
	s_waitcnt lgkmcnt(1)
	v_pk_fma_f32 v[36:37], v[2:3], v[28:29], v[74:75] op_sel_hi:[0,1,1]
	v_pk_mul_f32 v[6:7], v[6:7], v[52:53]
	v_add_u32_e32 v48, 0x400, v48
	v_mov_b32_e32 v61, v6
	s_waitcnt lgkmcnt(0)
	v_pk_fma_f32 v[28:29], v[2:3], v[8:9], v[16:17] op_sel_hi:[0,1,1]
	v_pk_add_f32 v[8:9], v[70:71], v[40:41]
	v_mov_b32_e32 v79, v7
	v_pk_add_f32 v[8:9], v[8:9], v[22:23]
	v_pk_fma_f32 v[38:39], v[2:3], v[30:31], v[76:77] op_sel_hi:[0,1,1]
	v_pk_add_f32 v[6:7], v[8:9], v[60:61]
	v_pk_fma_f32 v[30:31], v[2:3], v[10:11], v[58:59] op_sel_hi:[0,1,1]
	v_pk_fma_f32 v[16:17], v[2:3], v[50:51], v[80:81] op_sel_hi:[0,1,1]
	v_pk_add_f32 v[8:9], v[6:7], v[78:79]
	s_cbranch_scc0 .LBB0_12
	v_lshlrev_b32_e32 v2, 13, v47
	v_lshlrev_b32_e32 v4, 2, v46
	v_add3_u32 v2, 0, v2, v4
	s_add_u32 s34, s46, s16
	s_barrier
	ds_write2st64_b32 v2, v42, v43 offset1:1
	ds_write2st64_b32 v2, v44, v45 offset0:2 offset1:3
	ds_write2st64_b32 v2, v32, v33 offset0:4 offset1:5
	ds_write2st64_b32 v2, v34, v35 offset0:6 offset1:7
	ds_write2st64_b32 v2, v24, v25 offset0:8 offset1:9
	ds_write2st64_b32 v2, v26, v27 offset0:10 offset1:11
	ds_write2st64_b32 v2, v18, v19 offset0:12 offset1:13
	ds_write2st64_b32 v2, v20, v21 offset0:14 offset1:15
	ds_write2st64_b32 v2, v12, v13 offset0:16 offset1:17
	ds_write2st64_b32 v2, v14, v15 offset0:18 offset1:19
	ds_write2st64_b32 v2, v36, v37 offset0:20 offset1:21
	ds_write2st64_b32 v2, v38, v39 offset0:22 offset1:23
	ds_write2st64_b32 v2, v28, v29 offset0:24 offset1:25
	ds_write2st64_b32 v2, v30, v31 offset0:26 offset1:27
	ds_write2st64_b32 v2, v16, v17 offset0:28 offset1:29
	ds_write2st64_b32 v2, v8, v9 offset0:30 offset1:31
	s_waitcnt lgkmcnt(0)
	s_barrier
; __device__ __forceinline__ int lane_id_() { int l; asm volatile("v_mbcnt_lo_u32_b32 %0, -1, 0\n\tv_mbcnt_hi_u32_b32 %0, -1, %0" : "=v"(l)); return l; }
; #define F_ada_b INF(4)
; __device__ __forceinline__ void p0_prologue(const Ctx& F) {
;     ...
; #pragma unroll
;         for (int i = 0; i < 4; ++i) { const int o = (F.wid * 64 + lane_id_()) + NTHREADS * i, b = o >> 6, nn = o & 63; float s = F_ada_b[l * 6144 + n0 + nn];
; #pragma unroll
;             for (int p = 0; p < 8; ++p) s += red[(p * 32 + b) * 64 + nn];
;             mod[((size_t)l * 32 + b) * 6144 + n0 + nn] = s; }
;         __syncthreads();
;     }
	s_addc_u32 s35, s47, s17
	v_mbcnt_lo_u32_b32 v2, -1, 0
	v_mbcnt_hi_u32_b32 v2, -1, v2
	s_load_dwordx2 s[16:17], s[12:13], 0x20
	s_mul_i32 s15, s10, 0x1800
	s_add_i32 s33, s15, s14
	v_and_b32_e32 v6, 63, v2
	v_or_b32_e32 v4, s33, v6
	v_ashrrev_i32_e32 v5, 31, v4
	s_waitcnt lgkmcnt(0)
	v_lshl_add_u64 v[4:5], v[4:5], 2, s[16:17]
	flat_load_dword v18, v[4:5]
	v_add_u32_e32 v7, s0, v2
	v_and_b32_e32 v8, 0x3fffffc0, v7
	v_lshlrev_b32_e32 v2, 2, v6
	v_ashrrev_i32_e32 v6, 6, v7
	s_lshl_b64 s[10:11], s[10:11], 5
	v_lshlrev_b32_e32 v8, 2, v8
	v_ashrrev_i32_e32 v7, 31, v6
	v_mov_b64_e32 v[4:5], s[34:35]
	v_add3_u32 v14, 0, v8, v2
	v_lshl_add_u64 v[6:7], s[10:11], 0, v[6:7]
	ds_read2st64_b32 v[8:9], v14 offset1:32
	ds_read2st64_b32 v[10:11], v14 offset0:64 offset1:96
	ds_read2st64_b32 v[12:13], v14 offset0:128 offset1:160
	ds_read2st64_b32 v[14:15], v14 offset0:192 offset1:224
	v_mad_u64_u32 v[16:17], s[14:15], v6, s23, v[4:5]
	v_mad_i32_i24 v17, v7, s23, v17
	v_lshl_add_u64 v[6:7], v[16:17], 0, v[2:3]
	s_add_i32 s31, s31, s90
	s_cmpk_gt_i32 s31, 0xbf
	s_waitcnt vmcnt(0) lgkmcnt(0)
	v_add_f32_e32 v2, v18, v8
	v_add_f32_e32 v2, v2, v9
	v_add_f32_e32 v2, v2, v10
	v_add_f32_e32 v2, v2, v11
	v_add_f32_e32 v2, v2, v12
	v_add_f32_e32 v2, v2, v13
	v_add_f32_e32 v2, v2, v14
	v_add_f32_e32 v2, v2, v15
	global_store_dword v[6:7], v2, off
	v_mbcnt_lo_u32_b32 v2, -1, 0
	v_mbcnt_hi_u32_b32 v2, -1, v2
	s_nop 0
	v_and_b32_e32 v8, 63, v2
	v_or_b32_e32 v6, s33, v8
	v_ashrrev_i32_e32 v7, 31, v6
	v_lshl_add_u64 v[6:7], v[6:7], 2, s[16:17]
	flat_load_dword v18, v[6:7]
	v_add_u32_e32 v6, s1, v2
	v_and_b32_e32 v7, 0x3fffffc0, v6
	v_ashrrev_i32_e32 v6, 6, v6
	v_lshlrev_b32_e32 v2, 2, v8
	v_lshlrev_b32_e32 v8, 2, v7
	v_ashrrev_i32_e32 v7, 31, v6
	v_add3_u32 v14, 0, v8, v2
	v_lshl_add_u64 v[6:7], s[10:11], 0, v[6:7]
	ds_read2st64_b32 v[8:9], v14 offset1:32
	ds_read2st64_b32 v[10:11], v14 offset0:64 offset1:96
	ds_read2st64_b32 v[12:13], v14 offset0:128 offset1:160
	ds_read2st64_b32 v[14:15], v14 offset0:192 offset1:224
	v_mad_u64_u32 v[16:17], s[14:15], v6, s23, v[4:5]
	v_mad_i32_i24 v17, v7, s23, v17
	v_lshl_add_u64 v[6:7], v[16:17], 0, v[2:3]
	s_waitcnt vmcnt(0) lgkmcnt(0)
	v_add_f32_e32 v2, v18, v8
	v_add_f32_e32 v2, v2, v9
	v_add_f32_e32 v2, v2, v10
	v_add_f32_e32 v2, v2, v11
	v_add_f32_e32 v2, v2, v12
	v_add_f32_e32 v2, v2, v13
	v_add_f32_e32 v2, v2, v14
	v_add_f32_e32 v2, v2, v15
	global_store_dword v[6:7], v2, off
	v_mbcnt_lo_u32_b32 v2, -1, 0
	v_mbcnt_hi_u32_b32 v2, -1, v2
	s_nop 0
	v_and_b32_e32 v8, 63, v2
	v_or_b32_e32 v6, s33, v8
	v_ashrrev_i32_e32 v7, 31, v6
	v_lshl_add_u64 v[6:7], v[6:7], 2, s[16:17]
	flat_load_dword v18, v[6:7]
	v_add_u32_e32 v6, s3, v2
	v_and_b32_e32 v7, 0x3fffffc0, v6
	v_ashrrev_i32_e32 v6, 6, v6
	v_lshlrev_b32_e32 v2, 2, v8
	v_lshlrev_b32_e32 v8, 2, v7
	v_ashrrev_i32_e32 v7, 31, v6
	v_add3_u32 v14, 0, v8, v2
	v_lshl_add_u64 v[6:7], s[10:11], 0, v[6:7]
	ds_read2st64_b32 v[8:9], v14 offset1:32
	ds_read2st64_b32 v[10:11], v14 offset0:64 offset1:96
	ds_read2st64_b32 v[12:13], v14 offset0:128 offset1:160
	ds_read2st64_b32 v[14:15], v14 offset0:192 offset1:224
	v_mad_u64_u32 v[16:17], s[14:15], v6, s23, v[4:5]
	v_mad_i32_i24 v17, v7, s23, v17
	v_lshl_add_u64 v[6:7], v[16:17], 0, v[2:3]
	s_waitcnt vmcnt(0) lgkmcnt(0)
	v_add_f32_e32 v2, v18, v8
	v_add_f32_e32 v2, v2, v9
	v_add_f32_e32 v2, v2, v10
	v_add_f32_e32 v2, v2, v11
	v_add_f32_e32 v2, v2, v12
	v_add_f32_e32 v2, v2, v13
	v_add_f32_e32 v2, v2, v14
	v_add_f32_e32 v2, v2, v15
	global_store_dword v[6:7], v2, off
	v_mbcnt_lo_u32_b32 v2, -1, 0
	v_mbcnt_hi_u32_b32 v2, -1, v2
	s_nop 0
	v_and_b32_e32 v8, 63, v2
	v_or_b32_e32 v6, s33, v8
	v_ashrrev_i32_e32 v7, 31, v6
	v_lshl_add_u64 v[6:7], v[6:7], 2, s[16:17]
	flat_load_dword v16, v[6:7]
	v_add_u32_e32 v6, s18, v2
	v_and_b32_e32 v7, 0x3fffffc0, v6
	v_ashrrev_i32_e32 v6, 6, v6
	v_lshlrev_b32_e32 v2, 2, v8
	v_lshlrev_b32_e32 v8, 2, v7
	v_ashrrev_i32_e32 v7, 31, v6
	v_add3_u32 v14, 0, v8, v2
	v_lshl_add_u64 v[6:7], s[10:11], 0, v[6:7]
	ds_read2st64_b32 v[8:9], v14 offset1:32
	ds_read2st64_b32 v[10:11], v14 offset0:64 offset1:96
	ds_read2st64_b32 v[12:13], v14 offset0:128 offset1:160
	ds_read2st64_b32 v[14:15], v14 offset0:192 offset1:224
	v_mad_u64_u32 v[4:5], s[10:11], v6, s23, v[4:5]
	v_mad_i32_i24 v5, v7, s23, v5
	v_lshl_add_u64 v[4:5], v[4:5], 0, v[2:3]
	s_waitcnt vmcnt(0) lgkmcnt(0)
	v_add_f32_e32 v2, v16, v8
	v_add_f32_e32 v2, v2, v9
	v_add_f32_e32 v2, v2, v10
	v_add_f32_e32 v2, v2, v11
	v_add_f32_e32 v2, v2, v12
	v_add_f32_e32 v2, v2, v13
	v_add_f32_e32 v2, v2, v14
	v_add_f32_e32 v2, v2, v15
	global_store_dword v[4:5], v2, off
	s_barrier
	s_cbranch_scc0 .LBB0_8
